# scan recurrence: next-step LDS loads issued at step start, one counted wait per step
# speedup vs baseline: 1.0053x; 1.0053x over previous
.LBB0_545:
	s_waitcnt vmcnt(0)
	v_mbcnt_lo_u32_b32 v54, -1, 0
	v_mbcnt_hi_u32_b32 v54, -1, v54
	s_mul_i32 s4, s93, 0x6000
	v_and_b32_e32 v55, 15, v54
	v_lshrrev_b32_e32 v52, 4, v54
	v_and_b32_e32 v53, 1, v54
	v_lshl_add_u32 v2, v55, 4, s4
	v_lshl_add_u32 v52, v52, 1, v53
	s_lshl_b32 s5, s90, 2
	s_add_i32 s5, s5, s4
	s_add_i32 s5, s5, s59
	v_lshl_add_u32 v3, v52, 2, s5
	v_lshrrev_b32_e32 v55, 1, v55
	v_xor_b32_e32 v53, 4, v3
	v_lshlrev_b32_e32 v55, 2, v55
	s_lshl_b32 s4, s93, 14
	s_lshl_b32 s5, s59, 3
	s_add_i32 s4, s4, s5
	v_lshl_add_u32 v0, v52, 5, v55
	v_add_u32_e32 v0, s4, v0
	ds_read_b128 v[24:27], v2 offset:16384
	ds_read_b32 v44, v3 offset:12288
	ds_read_b32 v45, v53 offset:12288
	ds_read_b128 v[36:39], v2 offset:8192
	ds_read_b128 v[28:31], v2 offset:4096
	ds_read_b128 v[32:35], v2 offset:20480
	ds_read_b128 v[40:43], v2 offset:0
	ds_read_b128 v[144:147], v2 offset:16640
	ds_read_b32 v164, v3 offset:12544
	ds_read_b32 v165, v53 offset:12544
	ds_read_b128 v[156:159], v2 offset:8448
	ds_read_b128 v[148:151], v2 offset:4352
	ds_read_b128 v[152:155], v2 offset:20736
	s_waitcnt lgkmcnt(6)
	v_pk_mul_f32 v[46:47], v[16:17], v[24:25] op_sel_hi:[1,0]
	v_pk_fma_f32 v[46:47], v[18:19], v[24:25], v[46:47] op_sel:[0,1,0] op_sel_hi:[1,1,1]
	v_pk_fma_f32 v[46:47], v[20:21], v[26:27], v[46:47] op_sel_hi:[1,0,1]
	v_pk_fma_f32 v[46:47], v[22:23], v[26:27], v[46:47] op_sel:[0,1,0] op_sel_hi:[1,1,1]
	ds_read_b128 v[160:163], v2 offset:256
	v_pk_mul_f32 v[168:169], v[44:45], v[36:37] op_sel_hi:[1,0]
	v_add_f32_dpp v48, v47, v46 quad_perm:[1,0,3,2] row_mask:0xf bank_mask:0xf bound_ctrl:1
	v_pk_mul_f32 v[170:171], v[44:45], v[36:37] op_sel:[0,1] op_sel_hi:[1,1]
	s_nop 0
	v_add_f32_dpp v48, v48, v48 quad_perm:[2,3,0,1] row_mask:0xf bank_mask:0xf bound_ctrl:1
	v_pk_mul_f32 v[172:173], v[44:45], v[38:39] op_sel_hi:[1,0]
	v_pk_mul_f32 v[174:175], v[44:45], v[38:39] op_sel:[0,1] op_sel_hi:[1,1]
	v_add_f32_dpp v48, v48, v48 row_ror:4 row_mask:0xf bank_mask:0xf bound_ctrl:1
	v_pk_fma_f32 v[168:169], v[16:17], v[28:29], v[168:169] op_sel_hi:[1,0,1]
	v_pk_fma_f32 v[170:171], v[18:19], v[28:29], v[170:171] op_sel:[0,1,0] op_sel_hi:[1,1,1]
	v_add_f32_dpp v48, v48, v48 row_ror:8 row_mask:0xf bank_mask:0xf bound_ctrl:1
	v_pk_fma_f32 v[172:173], v[20:21], v[30:31], v[172:173] op_sel_hi:[1,0,1]
	v_pk_fma_f32 v[174:175], v[22:23], v[30:31], v[174:175] op_sel:[0,1,0] op_sel_hi:[1,1,1]
	v_mov_b32_dpp v49, v48 quad_perm:[1,0,3,2] row_mask:0xf bank_mask:0xf bound_ctrl:1
	v_pk_fma_f32 v[16:17], v[48:49], v[32:33], v[168:169] op_sel_hi:[1,0,1] neg_lo:[0,1,0] neg_hi:[0,1,0]
	v_pk_fma_f32 v[18:19], v[48:49], v[32:33], v[170:171] op_sel:[0,1,0] op_sel_hi:[1,1,1] neg_lo:[0,1,0] neg_hi:[0,1,0]
	v_pk_fma_f32 v[20:21], v[48:49], v[34:35], v[172:173] op_sel_hi:[1,0,1] neg_lo:[0,1,0] neg_hi:[0,1,0]
	v_pk_fma_f32 v[22:23], v[48:49], v[34:35], v[174:175] op_sel:[0,1,0] op_sel_hi:[1,1,1] neg_lo:[0,1,0] neg_hi:[0,1,0]
	ds_read_b128 v[24:27], v2 offset:16896
	ds_read_b32 v44, v3 offset:12800
	ds_read_b32 v45, v53 offset:12800
	ds_read_b128 v[36:39], v2 offset:8704
	ds_read_b128 v[28:31], v2 offset:4608
	ds_read_b128 v[32:35], v2 offset:20992
	s_waitcnt lgkmcnt(6)
	v_pk_mul_f32 v[46:47], v[16:17], v[144:145] op_sel_hi:[1,0]
	v_pk_mul_f32 v[50:51], v[16:17], v[40:41] op_sel_hi:[1,0]
	v_pk_fma_f32 v[46:47], v[18:19], v[144:145], v[46:47] op_sel:[0,1,0] op_sel_hi:[1,1,1]
	v_pk_fma_f32 v[50:51], v[18:19], v[40:41], v[50:51] op_sel:[0,1,0] op_sel_hi:[1,1,1]
	v_pk_fma_f32 v[46:47], v[20:21], v[146:147], v[46:47] op_sel_hi:[1,0,1]
	v_pk_fma_f32 v[50:51], v[20:21], v[42:43], v[50:51] op_sel_hi:[1,0,1]
	v_pk_fma_f32 v[46:47], v[22:23], v[146:147], v[46:47] op_sel:[0,1,0] op_sel_hi:[1,1,1]
	v_pk_fma_f32 v[50:51], v[22:23], v[42:43], v[50:51] op_sel:[0,1,0] op_sel_hi:[1,1,1]
	ds_read_b128 v[40:43], v2 offset:512
	v_pk_mul_f32 v[168:169], v[164:165], v[156:157] op_sel_hi:[1,0]
	v_add_f32_dpp v48, v47, v46 quad_perm:[1,0,3,2] row_mask:0xf bank_mask:0xf bound_ctrl:1
	v_add_f32_dpp v52, v51, v50 quad_perm:[1,0,3,2] row_mask:0xf bank_mask:0xf bound_ctrl:1
	v_pk_mul_f32 v[170:171], v[164:165], v[156:157] op_sel:[0,1] op_sel_hi:[1,1]
	v_add_f32_dpp v48, v48, v48 quad_perm:[2,3,0,1] row_mask:0xf bank_mask:0xf bound_ctrl:1
	ds_write_b32 v0, v52 offset:49152
	v_pk_mul_f32 v[172:173], v[164:165], v[158:159] op_sel_hi:[1,0]
	v_pk_mul_f32 v[174:175], v[164:165], v[158:159] op_sel:[0,1] op_sel_hi:[1,1]
	v_add_f32_dpp v48, v48, v48 row_ror:4 row_mask:0xf bank_mask:0xf bound_ctrl:1
	v_pk_fma_f32 v[168:169], v[16:17], v[148:149], v[168:169] op_sel_hi:[1,0,1]
	v_pk_fma_f32 v[170:171], v[18:19], v[148:149], v[170:171] op_sel:[0,1,0] op_sel_hi:[1,1,1]
	v_add_f32_dpp v48, v48, v48 row_ror:8 row_mask:0xf bank_mask:0xf bound_ctrl:1
	v_pk_fma_f32 v[172:173], v[20:21], v[150:151], v[172:173] op_sel_hi:[1,0,1]
	v_pk_fma_f32 v[174:175], v[22:23], v[150:151], v[174:175] op_sel:[0,1,0] op_sel_hi:[1,1,1]
	v_mov_b32_dpp v49, v48 quad_perm:[1,0,3,2] row_mask:0xf bank_mask:0xf bound_ctrl:1
	v_pk_fma_f32 v[16:17], v[48:49], v[152:153], v[168:169] op_sel_hi:[1,0,1] neg_lo:[0,1,0] neg_hi:[0,1,0]
	v_pk_fma_f32 v[18:19], v[48:49], v[152:153], v[170:171] op_sel:[0,1,0] op_sel_hi:[1,1,1] neg_lo:[0,1,0] neg_hi:[0,1,0]
	v_pk_fma_f32 v[20:21], v[48:49], v[154:155], v[172:173] op_sel_hi:[1,0,1] neg_lo:[0,1,0] neg_hi:[0,1,0]
	v_pk_fma_f32 v[22:23], v[48:49], v[154:155], v[174:175] op_sel:[0,1,0] op_sel_hi:[1,1,1] neg_lo:[0,1,0] neg_hi:[0,1,0]
	ds_read_b128 v[144:147], v2 offset:17152
	ds_read_b32 v164, v3 offset:13056
	ds_read_b32 v165, v53 offset:13056
	ds_read_b128 v[156:159], v2 offset:8960
	ds_read_b128 v[148:151], v2 offset:4864
	ds_read_b128 v[152:155], v2 offset:21248
	s_waitcnt lgkmcnt(7)
	v_pk_mul_f32 v[46:47], v[16:17], v[24:25] op_sel_hi:[1,0]
	v_pk_mul_f32 v[50:51], v[16:17], v[160:161] op_sel_hi:[1,0]
	v_pk_fma_f32 v[46:47], v[18:19], v[24:25], v[46:47] op_sel:[0,1,0] op_sel_hi:[1,1,1]
	v_pk_fma_f32 v[50:51], v[18:19], v[160:161], v[50:51] op_sel:[0,1,0] op_sel_hi:[1,1,1]
	v_pk_fma_f32 v[46:47], v[20:21], v[26:27], v[46:47] op_sel_hi:[1,0,1]
	v_pk_fma_f32 v[50:51], v[20:21], v[162:163], v[50:51] op_sel_hi:[1,0,1]
	v_pk_fma_f32 v[46:47], v[22:23], v[26:27], v[46:47] op_sel:[0,1,0] op_sel_hi:[1,1,1]
	v_pk_fma_f32 v[50:51], v[22:23], v[162:163], v[50:51] op_sel:[0,1,0] op_sel_hi:[1,1,1]
	ds_read_b128 v[160:163], v2 offset:768
	v_pk_mul_f32 v[168:169], v[44:45], v[36:37] op_sel_hi:[1,0]
	v_add_f32_dpp v48, v47, v46 quad_perm:[1,0,3,2] row_mask:0xf bank_mask:0xf bound_ctrl:1
	v_add_f32_dpp v52, v51, v50 quad_perm:[1,0,3,2] row_mask:0xf bank_mask:0xf bound_ctrl:1
	v_pk_mul_f32 v[170:171], v[44:45], v[36:37] op_sel:[0,1] op_sel_hi:[1,1]
	v_add_f32_dpp v48, v48, v48 quad_perm:[2,3,0,1] row_mask:0xf bank_mask:0xf bound_ctrl:1
	ds_write_b32 v0, v52 offset:50176
	v_pk_mul_f32 v[172:173], v[44:45], v[38:39] op_sel_hi:[1,0]
	v_pk_mul_f32 v[174:175], v[44:45], v[38:39] op_sel:[0,1] op_sel_hi:[1,1]
	v_add_f32_dpp v48, v48, v48 row_ror:4 row_mask:0xf bank_mask:0xf bound_ctrl:1
	v_pk_fma_f32 v[168:169], v[16:17], v[28:29], v[168:169] op_sel_hi:[1,0,1]
	v_pk_fma_f32 v[170:171], v[18:19], v[28:29], v[170:171] op_sel:[0,1,0] op_sel_hi:[1,1,1]
	v_add_f32_dpp v48, v48, v48 row_ror:8 row_mask:0xf bank_mask:0xf bound_ctrl:1
	v_pk_fma_f32 v[172:173], v[20:21], v[30:31], v[172:173] op_sel_hi:[1,0,1]
	v_pk_fma_f32 v[174:175], v[22:23], v[30:31], v[174:175] op_sel:[0,1,0] op_sel_hi:[1,1,1]
	v_mov_b32_dpp v49, v48 quad_perm:[1,0,3,2] row_mask:0xf bank_mask:0xf bound_ctrl:1
	v_pk_fma_f32 v[16:17], v[48:49], v[32:33], v[168:169] op_sel_hi:[1,0,1] neg_lo:[0,1,0] neg_hi:[0,1,0]
	v_pk_fma_f32 v[18:19], v[48:49], v[32:33], v[170:171] op_sel:[0,1,0] op_sel_hi:[1,1,1] neg_lo:[0,1,0] neg_hi:[0,1,0]
	v_pk_fma_f32 v[20:21], v[48:49], v[34:35], v[172:173] op_sel_hi:[1,0,1] neg_lo:[0,1,0] neg_hi:[0,1,0]
	v_pk_fma_f32 v[22:23], v[48:49], v[34:35], v[174:175] op_sel:[0,1,0] op_sel_hi:[1,1,1] neg_lo:[0,1,0] neg_hi:[0,1,0]
	ds_read_b128 v[24:27], v2 offset:17408
	ds_read_b32 v44, v3 offset:13312
	ds_read_b32 v45, v53 offset:13312
	ds_read_b128 v[36:39], v2 offset:9216
	ds_read_b128 v[28:31], v2 offset:5120
	ds_read_b128 v[32:35], v2 offset:21504
	s_waitcnt lgkmcnt(7)
	v_pk_mul_f32 v[46:47], v[16:17], v[144:145] op_sel_hi:[1,0]
	v_pk_mul_f32 v[50:51], v[16:17], v[40:41] op_sel_hi:[1,0]
	v_pk_fma_f32 v[46:47], v[18:19], v[144:145], v[46:47] op_sel:[0,1,0] op_sel_hi:[1,1,1]
	v_pk_fma_f32 v[50:51], v[18:19], v[40:41], v[50:51] op_sel:[0,1,0] op_sel_hi:[1,1,1]
	v_pk_fma_f32 v[46:47], v[20:21], v[146:147], v[46:47] op_sel_hi:[1,0,1]
	v_pk_fma_f32 v[50:51], v[20:21], v[42:43], v[50:51] op_sel_hi:[1,0,1]
	v_pk_fma_f32 v[46:47], v[22:23], v[146:147], v[46:47] op_sel:[0,1,0] op_sel_hi:[1,1,1]
	v_pk_fma_f32 v[50:51], v[22:23], v[42:43], v[50:51] op_sel:[0,1,0] op_sel_hi:[1,1,1]
	ds_read_b128 v[40:43], v2 offset:1024
	v_pk_mul_f32 v[168:169], v[164:165], v[156:157] op_sel_hi:[1,0]
	v_add_f32_dpp v48, v47, v46 quad_perm:[1,0,3,2] row_mask:0xf bank_mask:0xf bound_ctrl:1
	v_add_f32_dpp v52, v51, v50 quad_perm:[1,0,3,2] row_mask:0xf bank_mask:0xf bound_ctrl:1
	v_pk_mul_f32 v[170:171], v[164:165], v[156:157] op_sel:[0,1] op_sel_hi:[1,1]
	v_add_f32_dpp v48, v48, v48 quad_perm:[2,3,0,1] row_mask:0xf bank_mask:0xf bound_ctrl:1
	ds_write_b32 v0, v52 offset:51200
	v_pk_mul_f32 v[172:173], v[164:165], v[158:159] op_sel_hi:[1,0]
	v_pk_mul_f32 v[174:175], v[164:165], v[158:159] op_sel:[0,1] op_sel_hi:[1,1]
	v_add_f32_dpp v48, v48, v48 row_ror:4 row_mask:0xf bank_mask:0xf bound_ctrl:1
	v_pk_fma_f32 v[168:169], v[16:17], v[148:149], v[168:169] op_sel_hi:[1,0,1]
	v_pk_fma_f32 v[170:171], v[18:19], v[148:149], v[170:171] op_sel:[0,1,0] op_sel_hi:[1,1,1]
	v_add_f32_dpp v48, v48, v48 row_ror:8 row_mask:0xf bank_mask:0xf bound_ctrl:1
	v_pk_fma_f32 v[172:173], v[20:21], v[150:151], v[172:173] op_sel_hi:[1,0,1]
	v_pk_fma_f32 v[174:175], v[22:23], v[150:151], v[174:175] op_sel:[0,1,0] op_sel_hi:[1,1,1]
	v_mov_b32_dpp v49, v48 quad_perm:[1,0,3,2] row_mask:0xf bank_mask:0xf bound_ctrl:1
	v_pk_fma_f32 v[16:17], v[48:49], v[152:153], v[168:169] op_sel_hi:[1,0,1] neg_lo:[0,1,0] neg_hi:[0,1,0]
	v_pk_fma_f32 v[18:19], v[48:49], v[152:153], v[170:171] op_sel:[0,1,0] op_sel_hi:[1,1,1] neg_lo:[0,1,0] neg_hi:[0,1,0]
	v_pk_fma_f32 v[20:21], v[48:49], v[154:155], v[172:173] op_sel_hi:[1,0,1] neg_lo:[0,1,0] neg_hi:[0,1,0]
	v_pk_fma_f32 v[22:23], v[48:49], v[154:155], v[174:175] op_sel:[0,1,0] op_sel_hi:[1,1,1] neg_lo:[0,1,0] neg_hi:[0,1,0]
	ds_read_b128 v[144:147], v2 offset:17664
	ds_read_b32 v164, v3 offset:13568
	ds_read_b32 v165, v53 offset:13568
	ds_read_b128 v[156:159], v2 offset:9472
	ds_read_b128 v[148:151], v2 offset:5376
	ds_read_b128 v[152:155], v2 offset:21760
	s_waitcnt lgkmcnt(7)
	v_pk_mul_f32 v[46:47], v[16:17], v[24:25] op_sel_hi:[1,0]
	v_pk_mul_f32 v[50:51], v[16:17], v[160:161] op_sel_hi:[1,0]
	v_pk_fma_f32 v[46:47], v[18:19], v[24:25], v[46:47] op_sel:[0,1,0] op_sel_hi:[1,1,1]
	v_pk_fma_f32 v[50:51], v[18:19], v[160:161], v[50:51] op_sel:[0,1,0] op_sel_hi:[1,1,1]
	v_pk_fma_f32 v[46:47], v[20:21], v[26:27], v[46:47] op_sel_hi:[1,0,1]
	v_pk_fma_f32 v[50:51], v[20:21], v[162:163], v[50:51] op_sel_hi:[1,0,1]
	v_pk_fma_f32 v[46:47], v[22:23], v[26:27], v[46:47] op_sel:[0,1,0] op_sel_hi:[1,1,1]
	v_pk_fma_f32 v[50:51], v[22:23], v[162:163], v[50:51] op_sel:[0,1,0] op_sel_hi:[1,1,1]
	ds_read_b128 v[160:163], v2 offset:1280
	v_pk_mul_f32 v[168:169], v[44:45], v[36:37] op_sel_hi:[1,0]
	v_add_f32_dpp v48, v47, v46 quad_perm:[1,0,3,2] row_mask:0xf bank_mask:0xf bound_ctrl:1
	v_add_f32_dpp v52, v51, v50 quad_perm:[1,0,3,2] row_mask:0xf bank_mask:0xf bound_ctrl:1
	v_pk_mul_f32 v[170:171], v[44:45], v[36:37] op_sel:[0,1] op_sel_hi:[1,1]
	v_add_f32_dpp v48, v48, v48 quad_perm:[2,3,0,1] row_mask:0xf bank_mask:0xf bound_ctrl:1
	ds_write_b32 v0, v52 offset:52224
	v_pk_mul_f32 v[172:173], v[44:45], v[38:39] op_sel_hi:[1,0]
	v_pk_mul_f32 v[174:175], v[44:45], v[38:39] op_sel:[0,1] op_sel_hi:[1,1]
	v_add_f32_dpp v48, v48, v48 row_ror:4 row_mask:0xf bank_mask:0xf bound_ctrl:1
	v_pk_fma_f32 v[168:169], v[16:17], v[28:29], v[168:169] op_sel_hi:[1,0,1]
	v_pk_fma_f32 v[170:171], v[18:19], v[28:29], v[170:171] op_sel:[0,1,0] op_sel_hi:[1,1,1]
	v_add_f32_dpp v48, v48, v48 row_ror:8 row_mask:0xf bank_mask:0xf bound_ctrl:1
	v_pk_fma_f32 v[172:173], v[20:21], v[30:31], v[172:173] op_sel_hi:[1,0,1]
	v_pk_fma_f32 v[174:175], v[22:23], v[30:31], v[174:175] op_sel:[0,1,0] op_sel_hi:[1,1,1]
	v_mov_b32_dpp v49, v48 quad_perm:[1,0,3,2] row_mask:0xf bank_mask:0xf bound_ctrl:1
	v_pk_fma_f32 v[16:17], v[48:49], v[32:33], v[168:169] op_sel_hi:[1,0,1] neg_lo:[0,1,0] neg_hi:[0,1,0]
	v_pk_fma_f32 v[18:19], v[48:49], v[32:33], v[170:171] op_sel:[0,1,0] op_sel_hi:[1,1,1] neg_lo:[0,1,0] neg_hi:[0,1,0]
	v_pk_fma_f32 v[20:21], v[48:49], v[34:35], v[172:173] op_sel_hi:[1,0,1] neg_lo:[0,1,0] neg_hi:[0,1,0]
	v_pk_fma_f32 v[22:23], v[48:49], v[34:35], v[174:175] op_sel:[0,1,0] op_sel_hi:[1,1,1] neg_lo:[0,1,0] neg_hi:[0,1,0]
	ds_read_b128 v[24:27], v2 offset:17920
	ds_read_b32 v44, v3 offset:13824
	ds_read_b32 v45, v53 offset:13824
	ds_read_b128 v[36:39], v2 offset:9728
	ds_read_b128 v[28:31], v2 offset:5632
	ds_read_b128 v[32:35], v2 offset:22016
	s_waitcnt lgkmcnt(7)
	v_pk_mul_f32 v[46:47], v[16:17], v[144:145] op_sel_hi:[1,0]
	v_pk_mul_f32 v[50:51], v[16:17], v[40:41] op_sel_hi:[1,0]
	v_pk_fma_f32 v[46:47], v[18:19], v[144:145], v[46:47] op_sel:[0,1,0] op_sel_hi:[1,1,1]
	v_pk_fma_f32 v[50:51], v[18:19], v[40:41], v[50:51] op_sel:[0,1,0] op_sel_hi:[1,1,1]
	v_pk_fma_f32 v[46:47], v[20:21], v[146:147], v[46:47] op_sel_hi:[1,0,1]
	v_pk_fma_f32 v[50:51], v[20:21], v[42:43], v[50:51] op_sel_hi:[1,0,1]
	v_pk_fma_f32 v[46:47], v[22:23], v[146:147], v[46:47] op_sel:[0,1,0] op_sel_hi:[1,1,1]
	v_pk_fma_f32 v[50:51], v[22:23], v[42:43], v[50:51] op_sel:[0,1,0] op_sel_hi:[1,1,1]
	ds_read_b128 v[40:43], v2 offset:1536
	v_pk_mul_f32 v[168:169], v[164:165], v[156:157] op_sel_hi:[1,0]
	v_add_f32_dpp v48, v47, v46 quad_perm:[1,0,3,2] row_mask:0xf bank_mask:0xf bound_ctrl:1
	v_add_f32_dpp v52, v51, v50 quad_perm:[1,0,3,2] row_mask:0xf bank_mask:0xf bound_ctrl:1
	v_pk_mul_f32 v[170:171], v[164:165], v[156:157] op_sel:[0,1] op_sel_hi:[1,1]
	v_add_f32_dpp v48, v48, v48 quad_perm:[2,3,0,1] row_mask:0xf bank_mask:0xf bound_ctrl:1
	ds_write_b32 v0, v52 offset:53248
	v_pk_mul_f32 v[172:173], v[164:165], v[158:159] op_sel_hi:[1,0]
	v_pk_mul_f32 v[174:175], v[164:165], v[158:159] op_sel:[0,1] op_sel_hi:[1,1]
	v_add_f32_dpp v48, v48, v48 row_ror:4 row_mask:0xf bank_mask:0xf bound_ctrl:1
	v_pk_fma_f32 v[168:169], v[16:17], v[148:149], v[168:169] op_sel_hi:[1,0,1]
	v_pk_fma_f32 v[170:171], v[18:19], v[148:149], v[170:171] op_sel:[0,1,0] op_sel_hi:[1,1,1]
	v_add_f32_dpp v48, v48, v48 row_ror:8 row_mask:0xf bank_mask:0xf bound_ctrl:1
	v_pk_fma_f32 v[172:173], v[20:21], v[150:151], v[172:173] op_sel_hi:[1,0,1]
	v_pk_fma_f32 v[174:175], v[22:23], v[150:151], v[174:175] op_sel:[0,1,0] op_sel_hi:[1,1,1]
	v_mov_b32_dpp v49, v48 quad_perm:[1,0,3,2] row_mask:0xf bank_mask:0xf bound_ctrl:1
	v_pk_fma_f32 v[16:17], v[48:49], v[152:153], v[168:169] op_sel_hi:[1,0,1] neg_lo:[0,1,0] neg_hi:[0,1,0]
	v_pk_fma_f32 v[18:19], v[48:49], v[152:153], v[170:171] op_sel:[0,1,0] op_sel_hi:[1,1,1] neg_lo:[0,1,0] neg_hi:[0,1,0]
	v_pk_fma_f32 v[20:21], v[48:49], v[154:155], v[172:173] op_sel_hi:[1,0,1] neg_lo:[0,1,0] neg_hi:[0,1,0]
	v_pk_fma_f32 v[22:23], v[48:49], v[154:155], v[174:175] op_sel:[0,1,0] op_sel_hi:[1,1,1] neg_lo:[0,1,0] neg_hi:[0,1,0]
	ds_read_b128 v[144:147], v2 offset:18176
	ds_read_b32 v164, v3 offset:14080
	ds_read_b32 v165, v53 offset:14080
	ds_read_b128 v[156:159], v2 offset:9984
	ds_read_b128 v[148:151], v2 offset:5888
	ds_read_b128 v[152:155], v2 offset:22272
	s_waitcnt lgkmcnt(7)
	v_pk_mul_f32 v[46:47], v[16:17], v[24:25] op_sel_hi:[1,0]
	v_pk_mul_f32 v[50:51], v[16:17], v[160:161] op_sel_hi:[1,0]
	v_pk_fma_f32 v[46:47], v[18:19], v[24:25], v[46:47] op_sel:[0,1,0] op_sel_hi:[1,1,1]
	v_pk_fma_f32 v[50:51], v[18:19], v[160:161], v[50:51] op_sel:[0,1,0] op_sel_hi:[1,1,1]
	v_pk_fma_f32 v[46:47], v[20:21], v[26:27], v[46:47] op_sel_hi:[1,0,1]
	v_pk_fma_f32 v[50:51], v[20:21], v[162:163], v[50:51] op_sel_hi:[1,0,1]
	v_pk_fma_f32 v[46:47], v[22:23], v[26:27], v[46:47] op_sel:[0,1,0] op_sel_hi:[1,1,1]
	v_pk_fma_f32 v[50:51], v[22:23], v[162:163], v[50:51] op_sel:[0,1,0] op_sel_hi:[1,1,1]
	ds_read_b128 v[160:163], v2 offset:1792
	v_pk_mul_f32 v[168:169], v[44:45], v[36:37] op_sel_hi:[1,0]
	v_add_f32_dpp v48, v47, v46 quad_perm:[1,0,3,2] row_mask:0xf bank_mask:0xf bound_ctrl:1
	v_add_f32_dpp v52, v51, v50 quad_perm:[1,0,3,2] row_mask:0xf bank_mask:0xf bound_ctrl:1
	v_pk_mul_f32 v[170:171], v[44:45], v[36:37] op_sel:[0,1] op_sel_hi:[1,1]
	v_add_f32_dpp v48, v48, v48 quad_perm:[2,3,0,1] row_mask:0xf bank_mask:0xf bound_ctrl:1
	ds_write_b32 v0, v52 offset:54272
	v_pk_mul_f32 v[172:173], v[44:45], v[38:39] op_sel_hi:[1,0]
	v_pk_mul_f32 v[174:175], v[44:45], v[38:39] op_sel:[0,1] op_sel_hi:[1,1]
	v_add_f32_dpp v48, v48, v48 row_ror:4 row_mask:0xf bank_mask:0xf bound_ctrl:1
	v_pk_fma_f32 v[168:169], v[16:17], v[28:29], v[168:169] op_sel_hi:[1,0,1]
	v_pk_fma_f32 v[170:171], v[18:19], v[28:29], v[170:171] op_sel:[0,1,0] op_sel_hi:[1,1,1]
	v_add_f32_dpp v48, v48, v48 row_ror:8 row_mask:0xf bank_mask:0xf bound_ctrl:1
	v_pk_fma_f32 v[172:173], v[20:21], v[30:31], v[172:173] op_sel_hi:[1,0,1]
	v_pk_fma_f32 v[174:175], v[22:23], v[30:31], v[174:175] op_sel:[0,1,0] op_sel_hi:[1,1,1]
	v_mov_b32_dpp v49, v48 quad_perm:[1,0,3,2] row_mask:0xf bank_mask:0xf bound_ctrl:1
	v_pk_fma_f32 v[16:17], v[48:49], v[32:33], v[168:169] op_sel_hi:[1,0,1] neg_lo:[0,1,0] neg_hi:[0,1,0]
	v_pk_fma_f32 v[18:19], v[48:49], v[32:33], v[170:171] op_sel:[0,1,0] op_sel_hi:[1,1,1] neg_lo:[0,1,0] neg_hi:[0,1,0]
	v_pk_fma_f32 v[20:21], v[48:49], v[34:35], v[172:173] op_sel_hi:[1,0,1] neg_lo:[0,1,0] neg_hi:[0,1,0]
	v_pk_fma_f32 v[22:23], v[48:49], v[34:35], v[174:175] op_sel:[0,1,0] op_sel_hi:[1,1,1] neg_lo:[0,1,0] neg_hi:[0,1,0]
	ds_read_b128 v[24:27], v2 offset:18432
	ds_read_b32 v44, v3 offset:14336
	ds_read_b32 v45, v53 offset:14336
	ds_read_b128 v[36:39], v2 offset:10240
	ds_read_b128 v[28:31], v2 offset:6144
	ds_read_b128 v[32:35], v2 offset:22528
	s_waitcnt lgkmcnt(7)
	v_pk_mul_f32 v[46:47], v[16:17], v[144:145] op_sel_hi:[1,0]
	v_pk_mul_f32 v[50:51], v[16:17], v[40:41] op_sel_hi:[1,0]
	v_pk_fma_f32 v[46:47], v[18:19], v[144:145], v[46:47] op_sel:[0,1,0] op_sel_hi:[1,1,1]
	v_pk_fma_f32 v[50:51], v[18:19], v[40:41], v[50:51] op_sel:[0,1,0] op_sel_hi:[1,1,1]
	v_pk_fma_f32 v[46:47], v[20:21], v[146:147], v[46:47] op_sel_hi:[1,0,1]
	v_pk_fma_f32 v[50:51], v[20:21], v[42:43], v[50:51] op_sel_hi:[1,0,1]
	v_pk_fma_f32 v[46:47], v[22:23], v[146:147], v[46:47] op_sel:[0,1,0] op_sel_hi:[1,1,1]
	v_pk_fma_f32 v[50:51], v[22:23], v[42:43], v[50:51] op_sel:[0,1,0] op_sel_hi:[1,1,1]
	ds_read_b128 v[40:43], v2 offset:2048
	v_pk_mul_f32 v[168:169], v[164:165], v[156:157] op_sel_hi:[1,0]
	v_add_f32_dpp v48, v47, v46 quad_perm:[1,0,3,2] row_mask:0xf bank_mask:0xf bound_ctrl:1
	v_add_f32_dpp v52, v51, v50 quad_perm:[1,0,3,2] row_mask:0xf bank_mask:0xf bound_ctrl:1
	v_pk_mul_f32 v[170:171], v[164:165], v[156:157] op_sel:[0,1] op_sel_hi:[1,1]
	v_add_f32_dpp v48, v48, v48 quad_perm:[2,3,0,1] row_mask:0xf bank_mask:0xf bound_ctrl:1
	ds_write_b32 v0, v52 offset:55296
	v_pk_mul_f32 v[172:173], v[164:165], v[158:159] op_sel_hi:[1,0]
	v_pk_mul_f32 v[174:175], v[164:165], v[158:159] op_sel:[0,1] op_sel_hi:[1,1]
	v_add_f32_dpp v48, v48, v48 row_ror:4 row_mask:0xf bank_mask:0xf bound_ctrl:1
	v_pk_fma_f32 v[168:169], v[16:17], v[148:149], v[168:169] op_sel_hi:[1,0,1]
	v_pk_fma_f32 v[170:171], v[18:19], v[148:149], v[170:171] op_sel:[0,1,0] op_sel_hi:[1,1,1]
	v_add_f32_dpp v48, v48, v48 row_ror:8 row_mask:0xf bank_mask:0xf bound_ctrl:1
	v_pk_fma_f32 v[172:173], v[20:21], v[150:151], v[172:173] op_sel_hi:[1,0,1]
	v_pk_fma_f32 v[174:175], v[22:23], v[150:151], v[174:175] op_sel:[0,1,0] op_sel_hi:[1,1,1]
	v_mov_b32_dpp v49, v48 quad_perm:[1,0,3,2] row_mask:0xf bank_mask:0xf bound_ctrl:1
	v_pk_fma_f32 v[16:17], v[48:49], v[152:153], v[168:169] op_sel_hi:[1,0,1] neg_lo:[0,1,0] neg_hi:[0,1,0]
	v_pk_fma_f32 v[18:19], v[48:49], v[152:153], v[170:171] op_sel:[0,1,0] op_sel_hi:[1,1,1] neg_lo:[0,1,0] neg_hi:[0,1,0]
	v_pk_fma_f32 v[20:21], v[48:49], v[154:155], v[172:173] op_sel_hi:[1,0,1] neg_lo:[0,1,0] neg_hi:[0,1,0]
	v_pk_fma_f32 v[22:23], v[48:49], v[154:155], v[174:175] op_sel:[0,1,0] op_sel_hi:[1,1,1] neg_lo:[0,1,0] neg_hi:[0,1,0]
	ds_read_b128 v[144:147], v2 offset:18688
	ds_read_b32 v164, v3 offset:14592
	ds_read_b32 v165, v53 offset:14592
	ds_read_b128 v[156:159], v2 offset:10496
	ds_read_b128 v[148:151], v2 offset:6400
	ds_read_b128 v[152:155], v2 offset:22784
	s_waitcnt lgkmcnt(7)
	v_pk_mul_f32 v[46:47], v[16:17], v[24:25] op_sel_hi:[1,0]
	v_pk_mul_f32 v[50:51], v[16:17], v[160:161] op_sel_hi:[1,0]
	v_pk_fma_f32 v[46:47], v[18:19], v[24:25], v[46:47] op_sel:[0,1,0] op_sel_hi:[1,1,1]
	v_pk_fma_f32 v[50:51], v[18:19], v[160:161], v[50:51] op_sel:[0,1,0] op_sel_hi:[1,1,1]
	v_pk_fma_f32 v[46:47], v[20:21], v[26:27], v[46:47] op_sel_hi:[1,0,1]
	v_pk_fma_f32 v[50:51], v[20:21], v[162:163], v[50:51] op_sel_hi:[1,0,1]
	v_pk_fma_f32 v[46:47], v[22:23], v[26:27], v[46:47] op_sel:[0,1,0] op_sel_hi:[1,1,1]
	v_pk_fma_f32 v[50:51], v[22:23], v[162:163], v[50:51] op_sel:[0,1,0] op_sel_hi:[1,1,1]
	ds_read_b128 v[160:163], v2 offset:2304
	v_pk_mul_f32 v[168:169], v[44:45], v[36:37] op_sel_hi:[1,0]
	v_add_f32_dpp v48, v47, v46 quad_perm:[1,0,3,2] row_mask:0xf bank_mask:0xf bound_ctrl:1
	v_add_f32_dpp v52, v51, v50 quad_perm:[1,0,3,2] row_mask:0xf bank_mask:0xf bound_ctrl:1
	v_pk_mul_f32 v[170:171], v[44:45], v[36:37] op_sel:[0,1] op_sel_hi:[1,1]
	v_add_f32_dpp v48, v48, v48 quad_perm:[2,3,0,1] row_mask:0xf bank_mask:0xf bound_ctrl:1
	ds_write_b32 v0, v52 offset:56320
	v_pk_mul_f32 v[172:173], v[44:45], v[38:39] op_sel_hi:[1,0]
	v_pk_mul_f32 v[174:175], v[44:45], v[38:39] op_sel:[0,1] op_sel_hi:[1,1]
	v_add_f32_dpp v48, v48, v48 row_ror:4 row_mask:0xf bank_mask:0xf bound_ctrl:1
	v_pk_fma_f32 v[168:169], v[16:17], v[28:29], v[168:169] op_sel_hi:[1,0,1]
	v_pk_fma_f32 v[170:171], v[18:19], v[28:29], v[170:171] op_sel:[0,1,0] op_sel_hi:[1,1,1]
	v_add_f32_dpp v48, v48, v48 row_ror:8 row_mask:0xf bank_mask:0xf bound_ctrl:1
	v_pk_fma_f32 v[172:173], v[20:21], v[30:31], v[172:173] op_sel_hi:[1,0,1]
	v_pk_fma_f32 v[174:175], v[22:23], v[30:31], v[174:175] op_sel:[0,1,0] op_sel_hi:[1,1,1]
	v_mov_b32_dpp v49, v48 quad_perm:[1,0,3,2] row_mask:0xf bank_mask:0xf bound_ctrl:1
	v_pk_fma_f32 v[16:17], v[48:49], v[32:33], v[168:169] op_sel_hi:[1,0,1] neg_lo:[0,1,0] neg_hi:[0,1,0]
	v_pk_fma_f32 v[18:19], v[48:49], v[32:33], v[170:171] op_sel:[0,1,0] op_sel_hi:[1,1,1] neg_lo:[0,1,0] neg_hi:[0,1,0]
	v_pk_fma_f32 v[20:21], v[48:49], v[34:35], v[172:173] op_sel_hi:[1,0,1] neg_lo:[0,1,0] neg_hi:[0,1,0]
	v_pk_fma_f32 v[22:23], v[48:49], v[34:35], v[174:175] op_sel:[0,1,0] op_sel_hi:[1,1,1] neg_lo:[0,1,0] neg_hi:[0,1,0]
	ds_read_b128 v[24:27], v2 offset:18944
	ds_read_b32 v44, v3 offset:14848
	ds_read_b32 v45, v53 offset:14848
	ds_read_b128 v[36:39], v2 offset:10752
	ds_read_b128 v[28:31], v2 offset:6656
	ds_read_b128 v[32:35], v2 offset:23040
	s_waitcnt lgkmcnt(7)
	v_pk_mul_f32 v[46:47], v[16:17], v[144:145] op_sel_hi:[1,0]
	v_pk_mul_f32 v[50:51], v[16:17], v[40:41] op_sel_hi:[1,0]
	v_pk_fma_f32 v[46:47], v[18:19], v[144:145], v[46:47] op_sel:[0,1,0] op_sel_hi:[1,1,1]
	v_pk_fma_f32 v[50:51], v[18:19], v[40:41], v[50:51] op_sel:[0,1,0] op_sel_hi:[1,1,1]
	v_pk_fma_f32 v[46:47], v[20:21], v[146:147], v[46:47] op_sel_hi:[1,0,1]
	v_pk_fma_f32 v[50:51], v[20:21], v[42:43], v[50:51] op_sel_hi:[1,0,1]
	v_pk_fma_f32 v[46:47], v[22:23], v[146:147], v[46:47] op_sel:[0,1,0] op_sel_hi:[1,1,1]
	v_pk_fma_f32 v[50:51], v[22:23], v[42:43], v[50:51] op_sel:[0,1,0] op_sel_hi:[1,1,1]
	ds_read_b128 v[40:43], v2 offset:2560
	v_pk_mul_f32 v[168:169], v[164:165], v[156:157] op_sel_hi:[1,0]
	v_add_f32_dpp v48, v47, v46 quad_perm:[1,0,3,2] row_mask:0xf bank_mask:0xf bound_ctrl:1
	v_add_f32_dpp v52, v51, v50 quad_perm:[1,0,3,2] row_mask:0xf bank_mask:0xf bound_ctrl:1
	v_pk_mul_f32 v[170:171], v[164:165], v[156:157] op_sel:[0,1] op_sel_hi:[1,1]
	v_add_f32_dpp v48, v48, v48 quad_perm:[2,3,0,1] row_mask:0xf bank_mask:0xf bound_ctrl:1
	ds_write_b32 v0, v52 offset:57344
	v_pk_mul_f32 v[172:173], v[164:165], v[158:159] op_sel_hi:[1,0]
	v_pk_mul_f32 v[174:175], v[164:165], v[158:159] op_sel:[0,1] op_sel_hi:[1,1]
	v_add_f32_dpp v48, v48, v48 row_ror:4 row_mask:0xf bank_mask:0xf bound_ctrl:1
	v_pk_fma_f32 v[168:169], v[16:17], v[148:149], v[168:169] op_sel_hi:[1,0,1]
	v_pk_fma_f32 v[170:171], v[18:19], v[148:149], v[170:171] op_sel:[0,1,0] op_sel_hi:[1,1,1]
	v_add_f32_dpp v48, v48, v48 row_ror:8 row_mask:0xf bank_mask:0xf bound_ctrl:1
	v_pk_fma_f32 v[172:173], v[20:21], v[150:151], v[172:173] op_sel_hi:[1,0,1]
	v_pk_fma_f32 v[174:175], v[22:23], v[150:151], v[174:175] op_sel:[0,1,0] op_sel_hi:[1,1,1]
	v_mov_b32_dpp v49, v48 quad_perm:[1,0,3,2] row_mask:0xf bank_mask:0xf bound_ctrl:1
	v_pk_fma_f32 v[16:17], v[48:49], v[152:153], v[168:169] op_sel_hi:[1,0,1] neg_lo:[0,1,0] neg_hi:[0,1,0]
	v_pk_fma_f32 v[18:19], v[48:49], v[152:153], v[170:171] op_sel:[0,1,0] op_sel_hi:[1,1,1] neg_lo:[0,1,0] neg_hi:[0,1,0]
	v_pk_fma_f32 v[20:21], v[48:49], v[154:155], v[172:173] op_sel_hi:[1,0,1] neg_lo:[0,1,0] neg_hi:[0,1,0]
	v_pk_fma_f32 v[22:23], v[48:49], v[154:155], v[174:175] op_sel:[0,1,0] op_sel_hi:[1,1,1] neg_lo:[0,1,0] neg_hi:[0,1,0]
	ds_read_b128 v[144:147], v2 offset:19200
	ds_read_b32 v164, v3 offset:15104
	ds_read_b32 v165, v53 offset:15104
	ds_read_b128 v[156:159], v2 offset:11008
	ds_read_b128 v[148:151], v2 offset:6912
	ds_read_b128 v[152:155], v2 offset:23296
	s_waitcnt lgkmcnt(7)
	v_pk_mul_f32 v[46:47], v[16:17], v[24:25] op_sel_hi:[1,0]
	v_pk_mul_f32 v[50:51], v[16:17], v[160:161] op_sel_hi:[1,0]
	v_pk_fma_f32 v[46:47], v[18:19], v[24:25], v[46:47] op_sel:[0,1,0] op_sel_hi:[1,1,1]
	v_pk_fma_f32 v[50:51], v[18:19], v[160:161], v[50:51] op_sel:[0,1,0] op_sel_hi:[1,1,1]
	v_pk_fma_f32 v[46:47], v[20:21], v[26:27], v[46:47] op_sel_hi:[1,0,1]
	v_pk_fma_f32 v[50:51], v[20:21], v[162:163], v[50:51] op_sel_hi:[1,0,1]
	v_pk_fma_f32 v[46:47], v[22:23], v[26:27], v[46:47] op_sel:[0,1,0] op_sel_hi:[1,1,1]
	v_pk_fma_f32 v[50:51], v[22:23], v[162:163], v[50:51] op_sel:[0,1,0] op_sel_hi:[1,1,1]
	ds_read_b128 v[160:163], v2 offset:2816
	v_pk_mul_f32 v[168:169], v[44:45], v[36:37] op_sel_hi:[1,0]
	v_add_f32_dpp v48, v47, v46 quad_perm:[1,0,3,2] row_mask:0xf bank_mask:0xf bound_ctrl:1
	v_add_f32_dpp v52, v51, v50 quad_perm:[1,0,3,2] row_mask:0xf bank_mask:0xf bound_ctrl:1
	v_pk_mul_f32 v[170:171], v[44:45], v[36:37] op_sel:[0,1] op_sel_hi:[1,1]
	v_add_f32_dpp v48, v48, v48 quad_perm:[2,3,0,1] row_mask:0xf bank_mask:0xf bound_ctrl:1
	ds_write_b32 v0, v52 offset:58368
	v_pk_mul_f32 v[172:173], v[44:45], v[38:39] op_sel_hi:[1,0]
	v_pk_mul_f32 v[174:175], v[44:45], v[38:39] op_sel:[0,1] op_sel_hi:[1,1]
	v_add_f32_dpp v48, v48, v48 row_ror:4 row_mask:0xf bank_mask:0xf bound_ctrl:1
	v_pk_fma_f32 v[168:169], v[16:17], v[28:29], v[168:169] op_sel_hi:[1,0,1]
	v_pk_fma_f32 v[170:171], v[18:19], v[28:29], v[170:171] op_sel:[0,1,0] op_sel_hi:[1,1,1]
	v_add_f32_dpp v48, v48, v48 row_ror:8 row_mask:0xf bank_mask:0xf bound_ctrl:1
	v_pk_fma_f32 v[172:173], v[20:21], v[30:31], v[172:173] op_sel_hi:[1,0,1]
	v_pk_fma_f32 v[174:175], v[22:23], v[30:31], v[174:175] op_sel:[0,1,0] op_sel_hi:[1,1,1]
	v_mov_b32_dpp v49, v48 quad_perm:[1,0,3,2] row_mask:0xf bank_mask:0xf bound_ctrl:1
	v_pk_fma_f32 v[16:17], v[48:49], v[32:33], v[168:169] op_sel_hi:[1,0,1] neg_lo:[0,1,0] neg_hi:[0,1,0]
	v_pk_fma_f32 v[18:19], v[48:49], v[32:33], v[170:171] op_sel:[0,1,0] op_sel_hi:[1,1,1] neg_lo:[0,1,0] neg_hi:[0,1,0]
	v_pk_fma_f32 v[20:21], v[48:49], v[34:35], v[172:173] op_sel_hi:[1,0,1] neg_lo:[0,1,0] neg_hi:[0,1,0]
	v_pk_fma_f32 v[22:23], v[48:49], v[34:35], v[174:175] op_sel:[0,1,0] op_sel_hi:[1,1,1] neg_lo:[0,1,0] neg_hi:[0,1,0]
	ds_read_b128 v[24:27], v2 offset:19456
	ds_read_b32 v44, v3 offset:15360
	ds_read_b32 v45, v53 offset:15360
	ds_read_b128 v[36:39], v2 offset:11264
	ds_read_b128 v[28:31], v2 offset:7168
	ds_read_b128 v[32:35], v2 offset:23552
	s_waitcnt lgkmcnt(7)
	v_pk_mul_f32 v[46:47], v[16:17], v[144:145] op_sel_hi:[1,0]
	v_pk_mul_f32 v[50:51], v[16:17], v[40:41] op_sel_hi:[1,0]
	v_pk_fma_f32 v[46:47], v[18:19], v[144:145], v[46:47] op_sel:[0,1,0] op_sel_hi:[1,1,1]
	v_pk_fma_f32 v[50:51], v[18:19], v[40:41], v[50:51] op_sel:[0,1,0] op_sel_hi:[1,1,1]
	v_pk_fma_f32 v[46:47], v[20:21], v[146:147], v[46:47] op_sel_hi:[1,0,1]
	v_pk_fma_f32 v[50:51], v[20:21], v[42:43], v[50:51] op_sel_hi:[1,0,1]
	v_pk_fma_f32 v[46:47], v[22:23], v[146:147], v[46:47] op_sel:[0,1,0] op_sel_hi:[1,1,1]
	v_pk_fma_f32 v[50:51], v[22:23], v[42:43], v[50:51] op_sel:[0,1,0] op_sel_hi:[1,1,1]
	ds_read_b128 v[40:43], v2 offset:3072
	v_pk_mul_f32 v[168:169], v[164:165], v[156:157] op_sel_hi:[1,0]
	v_add_f32_dpp v48, v47, v46 quad_perm:[1,0,3,2] row_mask:0xf bank_mask:0xf bound_ctrl:1
	v_add_f32_dpp v52, v51, v50 quad_perm:[1,0,3,2] row_mask:0xf bank_mask:0xf bound_ctrl:1
	v_pk_mul_f32 v[170:171], v[164:165], v[156:157] op_sel:[0,1] op_sel_hi:[1,1]
	v_add_f32_dpp v48, v48, v48 quad_perm:[2,3,0,1] row_mask:0xf bank_mask:0xf bound_ctrl:1
	ds_write_b32 v0, v52 offset:59392
	v_pk_mul_f32 v[172:173], v[164:165], v[158:159] op_sel_hi:[1,0]
	v_pk_mul_f32 v[174:175], v[164:165], v[158:159] op_sel:[0,1] op_sel_hi:[1,1]
	v_add_f32_dpp v48, v48, v48 row_ror:4 row_mask:0xf bank_mask:0xf bound_ctrl:1
	v_pk_fma_f32 v[168:169], v[16:17], v[148:149], v[168:169] op_sel_hi:[1,0,1]
	v_pk_fma_f32 v[170:171], v[18:19], v[148:149], v[170:171] op_sel:[0,1,0] op_sel_hi:[1,1,1]
	v_add_f32_dpp v48, v48, v48 row_ror:8 row_mask:0xf bank_mask:0xf bound_ctrl:1
	v_pk_fma_f32 v[172:173], v[20:21], v[150:151], v[172:173] op_sel_hi:[1,0,1]
	v_pk_fma_f32 v[174:175], v[22:23], v[150:151], v[174:175] op_sel:[0,1,0] op_sel_hi:[1,1,1]
	v_mov_b32_dpp v49, v48 quad_perm:[1,0,3,2] row_mask:0xf bank_mask:0xf bound_ctrl:1
	v_pk_fma_f32 v[16:17], v[48:49], v[152:153], v[168:169] op_sel_hi:[1,0,1] neg_lo:[0,1,0] neg_hi:[0,1,0]
	v_pk_fma_f32 v[18:19], v[48:49], v[152:153], v[170:171] op_sel:[0,1,0] op_sel_hi:[1,1,1] neg_lo:[0,1,0] neg_hi:[0,1,0]
	v_pk_fma_f32 v[20:21], v[48:49], v[154:155], v[172:173] op_sel_hi:[1,0,1] neg_lo:[0,1,0] neg_hi:[0,1,0]
	v_pk_fma_f32 v[22:23], v[48:49], v[154:155], v[174:175] op_sel:[0,1,0] op_sel_hi:[1,1,1] neg_lo:[0,1,0] neg_hi:[0,1,0]
	ds_read_b128 v[144:147], v2 offset:19712
	ds_read_b32 v164, v3 offset:15616
	ds_read_b32 v165, v53 offset:15616
	ds_read_b128 v[156:159], v2 offset:11520
	ds_read_b128 v[148:151], v2 offset:7424
	ds_read_b128 v[152:155], v2 offset:23808
	s_waitcnt lgkmcnt(7)
	v_pk_mul_f32 v[46:47], v[16:17], v[24:25] op_sel_hi:[1,0]
	v_pk_mul_f32 v[50:51], v[16:17], v[160:161] op_sel_hi:[1,0]
	v_pk_fma_f32 v[46:47], v[18:19], v[24:25], v[46:47] op_sel:[0,1,0] op_sel_hi:[1,1,1]
	v_pk_fma_f32 v[50:51], v[18:19], v[160:161], v[50:51] op_sel:[0,1,0] op_sel_hi:[1,1,1]
	v_pk_fma_f32 v[46:47], v[20:21], v[26:27], v[46:47] op_sel_hi:[1,0,1]
	v_pk_fma_f32 v[50:51], v[20:21], v[162:163], v[50:51] op_sel_hi:[1,0,1]
	v_pk_fma_f32 v[46:47], v[22:23], v[26:27], v[46:47] op_sel:[0,1,0] op_sel_hi:[1,1,1]
	v_pk_fma_f32 v[50:51], v[22:23], v[162:163], v[50:51] op_sel:[0,1,0] op_sel_hi:[1,1,1]
	ds_read_b128 v[160:163], v2 offset:3328
	v_pk_mul_f32 v[168:169], v[44:45], v[36:37] op_sel_hi:[1,0]
	v_add_f32_dpp v48, v47, v46 quad_perm:[1,0,3,2] row_mask:0xf bank_mask:0xf bound_ctrl:1
	v_add_f32_dpp v52, v51, v50 quad_perm:[1,0,3,2] row_mask:0xf bank_mask:0xf bound_ctrl:1
	v_pk_mul_f32 v[170:171], v[44:45], v[36:37] op_sel:[0,1] op_sel_hi:[1,1]
	v_add_f32_dpp v48, v48, v48 quad_perm:[2,3,0,1] row_mask:0xf bank_mask:0xf bound_ctrl:1
	ds_write_b32 v0, v52 offset:60416
	v_pk_mul_f32 v[172:173], v[44:45], v[38:39] op_sel_hi:[1,0]
	v_pk_mul_f32 v[174:175], v[44:45], v[38:39] op_sel:[0,1] op_sel_hi:[1,1]
	v_add_f32_dpp v48, v48, v48 row_ror:4 row_mask:0xf bank_mask:0xf bound_ctrl:1
	v_pk_fma_f32 v[168:169], v[16:17], v[28:29], v[168:169] op_sel_hi:[1,0,1]
	v_pk_fma_f32 v[170:171], v[18:19], v[28:29], v[170:171] op_sel:[0,1,0] op_sel_hi:[1,1,1]
	v_add_f32_dpp v48, v48, v48 row_ror:8 row_mask:0xf bank_mask:0xf bound_ctrl:1
	v_pk_fma_f32 v[172:173], v[20:21], v[30:31], v[172:173] op_sel_hi:[1,0,1]
	v_pk_fma_f32 v[174:175], v[22:23], v[30:31], v[174:175] op_sel:[0,1,0] op_sel_hi:[1,1,1]
	v_mov_b32_dpp v49, v48 quad_perm:[1,0,3,2] row_mask:0xf bank_mask:0xf bound_ctrl:1
	v_pk_fma_f32 v[16:17], v[48:49], v[32:33], v[168:169] op_sel_hi:[1,0,1] neg_lo:[0,1,0] neg_hi:[0,1,0]
	v_pk_fma_f32 v[18:19], v[48:49], v[32:33], v[170:171] op_sel:[0,1,0] op_sel_hi:[1,1,1] neg_lo:[0,1,0] neg_hi:[0,1,0]
	v_pk_fma_f32 v[20:21], v[48:49], v[34:35], v[172:173] op_sel_hi:[1,0,1] neg_lo:[0,1,0] neg_hi:[0,1,0]
	v_pk_fma_f32 v[22:23], v[48:49], v[34:35], v[174:175] op_sel:[0,1,0] op_sel_hi:[1,1,1] neg_lo:[0,1,0] neg_hi:[0,1,0]
	ds_read_b128 v[24:27], v2 offset:19968
	ds_read_b32 v44, v3 offset:15872
	ds_read_b32 v45, v53 offset:15872
	ds_read_b128 v[36:39], v2 offset:11776
	ds_read_b128 v[28:31], v2 offset:7680
	ds_read_b128 v[32:35], v2 offset:24064
	s_waitcnt lgkmcnt(7)
	v_pk_mul_f32 v[46:47], v[16:17], v[144:145] op_sel_hi:[1,0]
	v_pk_mul_f32 v[50:51], v[16:17], v[40:41] op_sel_hi:[1,0]
	v_pk_fma_f32 v[46:47], v[18:19], v[144:145], v[46:47] op_sel:[0,1,0] op_sel_hi:[1,1,1]
	v_pk_fma_f32 v[50:51], v[18:19], v[40:41], v[50:51] op_sel:[0,1,0] op_sel_hi:[1,1,1]
	v_pk_fma_f32 v[46:47], v[20:21], v[146:147], v[46:47] op_sel_hi:[1,0,1]
	v_pk_fma_f32 v[50:51], v[20:21], v[42:43], v[50:51] op_sel_hi:[1,0,1]
	v_pk_fma_f32 v[46:47], v[22:23], v[146:147], v[46:47] op_sel:[0,1,0] op_sel_hi:[1,1,1]
	v_pk_fma_f32 v[50:51], v[22:23], v[42:43], v[50:51] op_sel:[0,1,0] op_sel_hi:[1,1,1]
	ds_read_b128 v[40:43], v2 offset:3584
	v_pk_mul_f32 v[168:169], v[164:165], v[156:157] op_sel_hi:[1,0]
	v_add_f32_dpp v48, v47, v46 quad_perm:[1,0,3,2] row_mask:0xf bank_mask:0xf bound_ctrl:1
	v_add_f32_dpp v52, v51, v50 quad_perm:[1,0,3,2] row_mask:0xf bank_mask:0xf bound_ctrl:1
	v_pk_mul_f32 v[170:171], v[164:165], v[156:157] op_sel:[0,1] op_sel_hi:[1,1]
	v_add_f32_dpp v48, v48, v48 quad_perm:[2,3,0,1] row_mask:0xf bank_mask:0xf bound_ctrl:1
	ds_write_b32 v0, v52 offset:61440
	v_pk_mul_f32 v[172:173], v[164:165], v[158:159] op_sel_hi:[1,0]
	v_pk_mul_f32 v[174:175], v[164:165], v[158:159] op_sel:[0,1] op_sel_hi:[1,1]
	v_add_f32_dpp v48, v48, v48 row_ror:4 row_mask:0xf bank_mask:0xf bound_ctrl:1
	v_pk_fma_f32 v[168:169], v[16:17], v[148:149], v[168:169] op_sel_hi:[1,0,1]
	v_pk_fma_f32 v[170:171], v[18:19], v[148:149], v[170:171] op_sel:[0,1,0] op_sel_hi:[1,1,1]
	v_add_f32_dpp v48, v48, v48 row_ror:8 row_mask:0xf bank_mask:0xf bound_ctrl:1
	v_pk_fma_f32 v[172:173], v[20:21], v[150:151], v[172:173] op_sel_hi:[1,0,1]
	v_pk_fma_f32 v[174:175], v[22:23], v[150:151], v[174:175] op_sel:[0,1,0] op_sel_hi:[1,1,1]
	v_mov_b32_dpp v49, v48 quad_perm:[1,0,3,2] row_mask:0xf bank_mask:0xf bound_ctrl:1
	v_pk_fma_f32 v[16:17], v[48:49], v[152:153], v[168:169] op_sel_hi:[1,0,1] neg_lo:[0,1,0] neg_hi:[0,1,0]
	v_pk_fma_f32 v[18:19], v[48:49], v[152:153], v[170:171] op_sel:[0,1,0] op_sel_hi:[1,1,1] neg_lo:[0,1,0] neg_hi:[0,1,0]
	v_pk_fma_f32 v[20:21], v[48:49], v[154:155], v[172:173] op_sel_hi:[1,0,1] neg_lo:[0,1,0] neg_hi:[0,1,0]
	v_pk_fma_f32 v[22:23], v[48:49], v[154:155], v[174:175] op_sel:[0,1,0] op_sel_hi:[1,1,1] neg_lo:[0,1,0] neg_hi:[0,1,0]
	ds_read_b128 v[144:147], v2 offset:20224
	ds_read_b32 v164, v3 offset:16128
	ds_read_b32 v165, v53 offset:16128
	ds_read_b128 v[156:159], v2 offset:12032
	ds_read_b128 v[148:151], v2 offset:7936
	ds_read_b128 v[152:155], v2 offset:24320
	s_waitcnt lgkmcnt(7)
	v_pk_mul_f32 v[46:47], v[16:17], v[24:25] op_sel_hi:[1,0]
	v_pk_mul_f32 v[50:51], v[16:17], v[160:161] op_sel_hi:[1,0]
	v_pk_fma_f32 v[46:47], v[18:19], v[24:25], v[46:47] op_sel:[0,1,0] op_sel_hi:[1,1,1]
	v_pk_fma_f32 v[50:51], v[18:19], v[160:161], v[50:51] op_sel:[0,1,0] op_sel_hi:[1,1,1]
	v_pk_fma_f32 v[46:47], v[20:21], v[26:27], v[46:47] op_sel_hi:[1,0,1]
	v_pk_fma_f32 v[50:51], v[20:21], v[162:163], v[50:51] op_sel_hi:[1,0,1]
	v_pk_fma_f32 v[46:47], v[22:23], v[26:27], v[46:47] op_sel:[0,1,0] op_sel_hi:[1,1,1]
	v_pk_fma_f32 v[50:51], v[22:23], v[162:163], v[50:51] op_sel:[0,1,0] op_sel_hi:[1,1,1]
	ds_read_b128 v[160:163], v2 offset:3840
	v_pk_mul_f32 v[168:169], v[44:45], v[36:37] op_sel_hi:[1,0]
	v_add_f32_dpp v48, v47, v46 quad_perm:[1,0,3,2] row_mask:0xf bank_mask:0xf bound_ctrl:1
	v_add_f32_dpp v52, v51, v50 quad_perm:[1,0,3,2] row_mask:0xf bank_mask:0xf bound_ctrl:1
	v_pk_mul_f32 v[170:171], v[44:45], v[36:37] op_sel:[0,1] op_sel_hi:[1,1]
	v_add_f32_dpp v48, v48, v48 quad_perm:[2,3,0,1] row_mask:0xf bank_mask:0xf bound_ctrl:1
	ds_write_b32 v0, v52 offset:62464
	v_pk_mul_f32 v[172:173], v[44:45], v[38:39] op_sel_hi:[1,0]
	v_pk_mul_f32 v[174:175], v[44:45], v[38:39] op_sel:[0,1] op_sel_hi:[1,1]
	v_add_f32_dpp v48, v48, v48 row_ror:4 row_mask:0xf bank_mask:0xf bound_ctrl:1
	v_pk_fma_f32 v[168:169], v[16:17], v[28:29], v[168:169] op_sel_hi:[1,0,1]
	v_pk_fma_f32 v[170:171], v[18:19], v[28:29], v[170:171] op_sel:[0,1,0] op_sel_hi:[1,1,1]
	v_add_f32_dpp v48, v48, v48 row_ror:8 row_mask:0xf bank_mask:0xf bound_ctrl:1
	v_pk_fma_f32 v[172:173], v[20:21], v[30:31], v[172:173] op_sel_hi:[1,0,1]
	v_pk_fma_f32 v[174:175], v[22:23], v[30:31], v[174:175] op_sel:[0,1,0] op_sel_hi:[1,1,1]
	v_mov_b32_dpp v49, v48 quad_perm:[1,0,3,2] row_mask:0xf bank_mask:0xf bound_ctrl:1
	v_pk_fma_f32 v[16:17], v[48:49], v[32:33], v[168:169] op_sel_hi:[1,0,1] neg_lo:[0,1,0] neg_hi:[0,1,0]
	v_pk_fma_f32 v[18:19], v[48:49], v[32:33], v[170:171] op_sel:[0,1,0] op_sel_hi:[1,1,1] neg_lo:[0,1,0] neg_hi:[0,1,0]
	v_pk_fma_f32 v[20:21], v[48:49], v[34:35], v[172:173] op_sel_hi:[1,0,1] neg_lo:[0,1,0] neg_hi:[0,1,0]
	v_pk_fma_f32 v[22:23], v[48:49], v[34:35], v[174:175] op_sel:[0,1,0] op_sel_hi:[1,1,1] neg_lo:[0,1,0] neg_hi:[0,1,0]
	s_waitcnt lgkmcnt(1)
	v_pk_mul_f32 v[46:47], v[16:17], v[144:145] op_sel_hi:[1,0]
	v_pk_mul_f32 v[50:51], v[16:17], v[40:41] op_sel_hi:[1,0]
	v_pk_fma_f32 v[46:47], v[18:19], v[144:145], v[46:47] op_sel:[0,1,0] op_sel_hi:[1,1,1]
	v_pk_fma_f32 v[50:51], v[18:19], v[40:41], v[50:51] op_sel:[0,1,0] op_sel_hi:[1,1,1]
	v_pk_fma_f32 v[46:47], v[20:21], v[146:147], v[46:47] op_sel_hi:[1,0,1]
	v_pk_fma_f32 v[50:51], v[20:21], v[42:43], v[50:51] op_sel_hi:[1,0,1]
	v_pk_fma_f32 v[46:47], v[22:23], v[146:147], v[46:47] op_sel:[0,1,0] op_sel_hi:[1,1,1]
	v_pk_fma_f32 v[50:51], v[22:23], v[42:43], v[50:51] op_sel:[0,1,0] op_sel_hi:[1,1,1]
	v_pk_mul_f32 v[168:169], v[164:165], v[156:157] op_sel_hi:[1,0]
	v_add_f32_dpp v48, v47, v46 quad_perm:[1,0,3,2] row_mask:0xf bank_mask:0xf bound_ctrl:1
	v_add_f32_dpp v52, v51, v50 quad_perm:[1,0,3,2] row_mask:0xf bank_mask:0xf bound_ctrl:1
	v_pk_mul_f32 v[170:171], v[164:165], v[156:157] op_sel:[0,1] op_sel_hi:[1,1]
	v_add_f32_dpp v48, v48, v48 quad_perm:[2,3,0,1] row_mask:0xf bank_mask:0xf bound_ctrl:1
	ds_write_b32 v0, v52 offset:63488
	v_pk_mul_f32 v[172:173], v[164:165], v[158:159] op_sel_hi:[1,0]
	v_pk_mul_f32 v[174:175], v[164:165], v[158:159] op_sel:[0,1] op_sel_hi:[1,1]
	v_add_f32_dpp v48, v48, v48 row_ror:4 row_mask:0xf bank_mask:0xf bound_ctrl:1
	v_pk_fma_f32 v[168:169], v[16:17], v[148:149], v[168:169] op_sel_hi:[1,0,1]
	v_pk_fma_f32 v[170:171], v[18:19], v[148:149], v[170:171] op_sel:[0,1,0] op_sel_hi:[1,1,1]
	v_add_f32_dpp v48, v48, v48 row_ror:8 row_mask:0xf bank_mask:0xf bound_ctrl:1
	v_pk_fma_f32 v[172:173], v[20:21], v[150:151], v[172:173] op_sel_hi:[1,0,1]
	v_pk_fma_f32 v[174:175], v[22:23], v[150:151], v[174:175] op_sel:[0,1,0] op_sel_hi:[1,1,1]
	v_mov_b32_dpp v49, v48 quad_perm:[1,0,3,2] row_mask:0xf bank_mask:0xf bound_ctrl:1
	v_pk_fma_f32 v[16:17], v[48:49], v[152:153], v[168:169] op_sel_hi:[1,0,1] neg_lo:[0,1,0] neg_hi:[0,1,0]
	v_pk_fma_f32 v[18:19], v[48:49], v[152:153], v[170:171] op_sel:[0,1,0] op_sel_hi:[1,1,1] neg_lo:[0,1,0] neg_hi:[0,1,0]
	v_pk_fma_f32 v[20:21], v[48:49], v[154:155], v[172:173] op_sel_hi:[1,0,1] neg_lo:[0,1,0] neg_hi:[0,1,0]
	v_pk_fma_f32 v[22:23], v[48:49], v[154:155], v[174:175] op_sel:[0,1,0] op_sel_hi:[1,1,1] neg_lo:[0,1,0] neg_hi:[0,1,0]
	v_pk_mul_f32 v[50:51], v[16:17], v[160:161] op_sel_hi:[1,0]
	v_pk_fma_f32 v[50:51], v[18:19], v[160:161], v[50:51] op_sel:[0,1,0] op_sel_hi:[1,1,1]
	v_pk_fma_f32 v[50:51], v[20:21], v[162:163], v[50:51] op_sel_hi:[1,0,1]
	v_pk_fma_f32 v[50:51], v[22:23], v[162:163], v[50:51] op_sel:[0,1,0] op_sel_hi:[1,1,1]
	s_nop 1
	v_add_f32_dpp v52, v51, v50 quad_perm:[1,0,3,2] row_mask:0xf bank_mask:0xf bound_ctrl:1
	ds_write_b32 v0, v52 offset:64512
